# v33 + mixscan chains start staggered by batch index (b x ~0.4us) to decorrelate the DRAM rows touched by the eight batches
# baseline (speedup 1.0000x reference)
.LBB0_343:
	s_bfe_u32 s36, s65, 0x30003
.Lstg_loop:
	s_cmp_eq_u32 s36, 0
	s_cbranch_scc1 .Lstg_done
	s_sleep 13
	s_sub_u32 s36, s36, 1
	s_branch .Lstg_loop
